# attention one-barrier loop: bank-0 completion DMAs issued at unit prologue start (prologue K tile 0 moved to LDS 0x8000), counted lgkm waits at the former mid-iteration barrier
# speedup vs baseline: 1.0084x; 1.0077x over previous
; #define LDSP __attribute__((address_space(3)))
; DI void attn_unit(const Params& p, int l, int b, int kvh, int qb, bool isctx, ldsp_t smem) {
;     int tid = threadIdx.x;
;     asm volatile("" : "+v"(tid));
;     const int wid = tid >> 6, lane = tid & 63, r = lane & 31, hh = lane >> 5;
;     const int head = kvh * 4 + (wid >> 1);
;     const int t0 = qb * 64 + (wid & 1) * 32;
;     const int nkeys = isctx ? CTXL : NKEY;
;     const bf16_t* Qp = isctx ? p.Qc + ((size_t)(b * 8 + head) * CTXL + t0) * 64 : p.Q + ((size_t)(b * 8 + head) * SEQ + t0) * 64;
;     const bf16_t* Kp = p.K + (size_t)(b * 2 + kvh) * NKEY * 64;
;     const bf16_t* Vp = p.Vt + (size_t)(b * 2 + kvh) * 64 * NKEY;
;     const int orow = isctx ? NLAT + b * CTXL + t0 : b * SEQ + t0;
;     bf16_t* Op = p.MIX + (size_t)orow * DM + head * 64;
;     const float cexp = p.smax[l] * LOG2E;
;     bf16x8 qf[4];
; #pragma unroll
;     for (int ks = 0; ks < 4; ++ks) qf[ks] = *(const bf16x8*)(Qp + (size_t)r * 64 + ks * 16 + 8 * hh);
;     f32x16 o[2];
; #pragma unroll
;     for (int i = 0; i < 16; ++i) { o[0][i] = 0.f; o[1][i] = 0.f; }
;     float rs0 = 0.f, rs1 = 0.f;
;     const int srow = tid >> 3, sch = tid & 7;
;     const int kdst = srow * 128 + ((sch ^ ((srow >> 1) & 7)) << 4);
;     const bf16_t* kg = Kp + (size_t)srow * 64 + sch * 8;
;     const bf16_t* vg = Vp + (size_t)srow * NKEY + sch * 8;
;     const int rsw = (r >> 1) & 7;
;     const int ntile = nkeys / 64;
;     ...
;     u32x4 kst, vst;
;     f32x16 sA[2], sB[2];
;     {
;         kst = *(const u32x4*)kg;
;         *(LDSP u32x4*)(smem + kdst) = kst;
;         kst = *(const u32x4*)(kg + (size_t)64 * 64);
;         vst = *(const u32x4*)vg;
;         __syncthreads();
;         ATT_QK(sA, smem);
;         *(LDSP u32x4*)(smem + 8192 + kdst) = kst;
;         *(LDSP u32x4*)(smem + 16384 + kdst) = vst;
;     }
.LBB0_163:
	v_mov_b32_e32 v24, v252
	s_lshl_b32 s9, s6, 2
	s_and_b32 s9, s9, 4
	v_ashrrev_i32_e32 v0, 7, v24
	v_add_u32_e32 v166, s9, v0
	s_lshl_b32 s9, s6, 3
	s_andn2_b32 s9, s9, 63
	v_lshrrev_b32_e32 v0, 1, v24
	v_and_or_b32 v144, v0, 32, s9
	s_and_b32 s9, s6, 7
	s_bfe_u32 s7, s6, 0x20001
	s_mul_i32 s98, s9, 0x88000
	v_ashrrev_i32_e32 v20, 3, v24
	s_add_u32 s10, s24, s98
	v_ashrrev_i32_e32 v21, 31, v20
	s_addc_u32 s11, s25, 0
	v_lshlrev_b32_e32 v10, 4, v24
	v_lshlrev_b64 v[0:1], 7, v[20:21]
	v_lshl_add_u64 v[0:1], s[10:11], 0, v[0:1]
	s_waitcnt lgkmcnt(5)
	v_and_b32_e32 v4, 0x70, v10
	s_waitcnt lgkmcnt(0)
	v_mov_b32_e32 v5, v193
	v_lshl_add_u64 v[146:147], v[0:1], 0, v[4:5]
	global_load_dwordx4 v[0:3], v[146:147], off
	global_load_dword v12, v193, s[4:5]
	v_lshl_add_u32 v6, s7, 3, v166
	v_ashrrev_i32_e32 v7, 31, v6
	v_ashrrev_i32_e32 v145, 31, v144
	v_lshlrev_b64 v[6:7], 19, v[6:7]
	v_and_b32_e32 v165, 31, v24
	v_lshlrev_b64 v[8:9], 7, v[144:145]
	v_lshl_add_u64 v[6:7], s[20:21], 0, v[6:7]
	v_bfe_u32 v164, v24, 5, 1
	v_lshl_add_u64 v[6:7], v[6:7], 0, v[8:9]
	v_lshlrev_b32_e32 v192, 7, v165
	v_lshl_add_u64 v[6:7], v[6:7], 0, v[192:193]
	v_lshlrev_b32_e32 v8, 4, v164
	v_mov_b32_e32 v9, v193
	v_lshl_add_u64 v[6:7], v[6:7], 0, v[8:9]
	global_load_dwordx4 v[112:115], v[6:7], off
	global_load_dwordx4 v[116:119], v[6:7], off offset:32
	global_load_dwordx4 v[120:123], v[6:7], off offset:64
	global_load_dwordx4 v[124:127], v[6:7], off offset:96
	v_lshrrev_b32_e32 v8, 5, v24
	v_bfe_u32 v16, v24, 1, 3
	s_add_u32 s10, s26, s98
	v_lshlrev_b32_e32 v9, 7, v20
	v_xor_b32_e32 v10, v10, v24
	v_bitop3_b32 v8, v8, v16, 1 bitop3:0x6c
	s_addc_u32 s11, s27, 0
	s_movk_i32 s9, 0x2000
	v_and_or_b32 v145, v10, s14, v9
	v_lshlrev_b32_e32 v167, 4, v8
	v_mov_b64_e32 v[8:9], s[10:11]
	s_movk_i32 s31, 0x2200
	v_add_co_u32_e32 v6, vcc, s9, v146
	v_mad_i64_i32 v[8:9], s[10:11], v20, s31, v[8:9]
	s_nop 0
	v_addc_co_u32_e32 v7, vcc, 0, v147, vcc
	v_lshl_add_u64 v[148:149], v[8:9], 0, v[4:5]
	global_load_dwordx4 v[4:7], v[6:7], off
	s_nop 0
	global_load_dwordx4 v[8:11], v[148:149], off
	v_and_b32_e32 v128, 7, v252
	v_bfe_u32 v129, v252, 4, 3
	v_xor_b32_e32 v129, v128, v129
	v_sub_u32_e32 v128, v129, v128
	v_lshlrev_b32_e32 v128, 4, v128
	v_add_u32_e32 v130, 0x4000, v128
	v_mov_b32_e32 v131, 0
	v_lshl_add_u64 v[130:131], v[146:147], 0, v[130:131]
	v_add_u32_e32 v132, 0x80, v128
	v_mov_b32_e32 v133, 0
	v_lshl_add_u64 v[132:133], v[148:149], 0, v[132:133]
	v_lshrrev_b32_e32 v134, 6, v252
	v_lshlrev_b32_e32 v134, 10, v134
	s_nop 0
	v_readfirstlane_b32 s100, v134
	s_nop 3
	s_mov_b32 m0, s100
	s_nop 0
	global_load_lds_dwordx4 v[130:131], off
	s_add_u32 m0, s100, 0x6000
	s_nop 0
	global_load_lds_dwordx4 v[132:133], off
	v_or_b32_e32 v13, v192, v167
	v_mov_b64_e32 v[22:23], s[98:99]
	s_mov_b32 s9, -2
	s_movk_i32 s91, 0x2200
	s_waitcnt vmcnt(9)
	ds_write_b128 v145, v[0:3] offset:32768
	s_waitcnt lgkmcnt(0)
	s_barrier
	ds_read_b128 v[0:3], v13 offset:32768
	s_waitcnt vmcnt(8)
	v_mul_f32_e32 v32, 0xbfb8aa3b, v12
	ds_read_b128 v[12:15], v13 offset:36864
	v_mov_b32_e32 v33, v32
	v_mov_b32_e32 v34, v32
	v_mov_b32_e32 v35, v32
	v_mov_b32_e32 v36, v32
	v_mov_b32_e32 v37, v32
	v_mov_b32_e32 v38, v32
	v_mov_b32_e32 v39, v32
	v_mov_b32_e32 v40, v32
	v_mov_b32_e32 v41, v32
	v_mov_b32_e32 v42, v32
	v_mov_b32_e32 v43, v32
	v_mov_b32_e32 v44, v32
	v_mov_b32_e32 v45, v32
	v_mov_b32_e32 v46, v32
	v_mov_b32_e32 v47, v32
	s_waitcnt vmcnt(7) lgkmcnt(1)
	s_nop 0
	v_mfma_f32_32x32x16_bf16 v[64:79], v[0:3], v[112:115], v[32:47]
	v_bitop3_b32 v0, v164, v16, 2 bitop3:0x36
	v_lshlrev_b32_e32 v168, 4, v0
	v_or_b32_e32 v17, v192, v168
	s_waitcnt lgkmcnt(0)
	v_mfma_f32_32x32x16_bf16 v[48:63], v[12:15], v[112:115], v[32:47]
	ds_read_b128 v[0:3], v17 offset:32768
	ds_read_b128 v[12:15], v17 offset:36864
	s_waitcnt vmcnt(6) lgkmcnt(1)
	v_mfma_f32_32x32x16_bf16 v[64:79], v[0:3], v[116:119], v[64:79]
	v_bitop3_b32 v0, v164, v16, 4 bitop3:0x36
	v_lshlrev_b32_e32 v169, 4, v0
	v_or_b32_e32 v17, v192, v169
	s_waitcnt lgkmcnt(0)
	v_mfma_f32_32x32x16_bf16 v[48:63], v[12:15], v[116:119], v[48:63]
	ds_read_b128 v[0:3], v17 offset:32768
	ds_read_b128 v[12:15], v17 offset:36864
	s_waitcnt vmcnt(5) lgkmcnt(1)
	v_mfma_f32_32x32x16_bf16 v[64:79], v[0:3], v[120:123], v[64:79]
	v_bitop3_b32 v0, v164, v16, 6 bitop3:0x36
	v_lshlrev_b32_e32 v170, 4, v0
	v_or_b32_e32 v21, v192, v170
	ds_read_b128 v[0:3], v21 offset:32768
	v_mov_b32_e32 v16, 0
	v_mov_b32_e32 v17, v16
	v_mov_b32_e32 v18, v16
	s_waitcnt lgkmcnt(1)
	v_mfma_f32_32x32x16_bf16 v[48:63], v[12:15], v[120:123], v[48:63]
	ds_read_b128 v[12:15], v21 offset:36864
	v_mov_b32_e32 v19, v16
	s_waitcnt vmcnt(3)
	ds_write_b128 v145, v[4:7] offset:8192
	s_waitcnt vmcnt(2)
	ds_write_b128 v145, v[8:11] offset:16384
	v_mov_b32_e32 v21, v16
	v_mov_b32_e32 v25, v16
	v_mov_b32_e32 v26, v16
	v_mov_b32_e32 v27, v16
	s_waitcnt lgkmcnt(3)
	v_mfma_f32_32x32x16_bf16 v[64:79], v[0:3], v[124:127], v[64:79]
	v_and_b32_e32 v2, 7, v24
	v_mad_i64_i32 v[0:1], s[10:11], v20, s31, v[22:23]
	v_lshl_or_b32 v0, v2, 4, v0
	v_lshl_add_u64 v[150:151], s[12:13], 0, v[0:1]
	v_mov_b32_e32 v20, v16
	v_mov_b32_e32 v22, v16
	s_waitcnt lgkmcnt(2)
	v_mfma_f32_32x32x16_bf16 v[48:63], v[12:15], v[124:127], v[48:63]
	v_mov_b32_e32 v23, v16
	v_mov_b32_e32 v24, v16
	v_mov_b32_e32 v28, v16
	v_mov_b32_e32 v29, v16
	v_mov_b32_e32 v30, v16
	v_mov_b32_e32 v31, v16
	v_mov_b32_e32 v0, v16
	v_mov_b32_e32 v1, v16
	v_mov_b32_e32 v2, v16
	v_mov_b32_e32 v3, v16
	v_mov_b32_e32 v4, v16
	v_mov_b32_e32 v5, v16
	v_mov_b32_e32 v6, v16
	v_mov_b32_e32 v7, v16
	v_mov_b32_e32 v8, v16
	v_mov_b32_e32 v9, v16
	v_mov_b32_e32 v10, v16
	v_mov_b32_e32 v11, v16
	v_mov_b32_e32 v12, v16
	v_mov_b32_e32 v13, v16
	v_mov_b32_e32 v14, v16
	v_mov_b32_e32 v15, v16
	v_mov_b32_e32 v136, v16
	v_mov_b32_e32 v137, v16
	v_and_b32_e32 v128, 7, v252
	v_bfe_u32 v129, v252, 4, 3
	v_xor_b32_e32 v129, v128, v129
	v_sub_u32_e32 v128, v129, v128
	v_lshlrev_b32_e32 v128, 4, v128
	v_ashrrev_i32_e32 v129, 31, v128
	v_lshrrev_b32_e32 v130, 6, v252
	v_lshlrev_b32_e32 v130, 10, v130
	v_lshl_add_u64 v[146:147], v[146:147], 0, v[128:129]
	v_lshl_add_u64 v[148:149], v[148:149], 0, v[128:129]
	v_lshl_add_u64 v[150:151], v[150:151], 0, v[128:129]
	v_readfirstlane_b32 s100, v130
	s_nop 3
	s_xor_b32 s101, s100, 0x18000
	v_mov_b32_e32 v128, 0x80
	v_mov_b32_e32 v129, 0
	v_lshl_add_u64 v[150:151], v[150:151], 0, v[128:129]
	.p2align	6
.LBB0_164:
	s_add_i32 s10, s9, 5
	s_min_u32 s10, s10, 0x43
	s_lshl_b32 s98, s10, 13
	v_lshl_add_u64 v[128:129], v[146:147], 0, s[98:99]
	s_add_i32 s11, s9, 6
	s_min_u32 s11, s11, 0x43
	s_lshl_b32 s98, s11, 13
	v_lshl_add_u64 v[130:131], v[146:147], 0, s[98:99]
	s_lshl_b32 s98, s10, 7
	v_lshl_add_u64 v[132:133], v[148:149], 0, s[98:99]
	s_waitcnt vmcnt(0)
	s_waitcnt lgkmcnt(0)
	s_barrier
	v_add_u32_e32 v171, v192, v167
	v_add_u32_e32 v172, v192, v168
	v_add_u32_e32 v142, v192, v169
	v_add_u32_e32 v143, v192, v170
	ds_read_b128 v[80:83], v171 offset:8192
	ds_read_b128 v[138:141], v171 offset:12288
	ds_read_b128 v[152:155], v172 offset:8192
	ds_read_b128 v[156:159], v172 offset:12288
	ds_read_b128 v[160:163], v142 offset:8192
	ds_read_b128 v[174:177], v142 offset:12288
	ds_read_b128 v[178:181], v143 offset:8192
	ds_read_b128 v[182:185], v143 offset:12288
	ds_read_b128 v[186:189], v171 offset:16384
	ds_read_b128 v[194:197], v171 offset:20480
	ds_read_b128 v[198:201], v172 offset:16384
	ds_read_b128 v[204:207], v172 offset:20480
	s_add_i32 s9, s9, 2
	s_waitcnt lgkmcnt(11)
	v_mfma_f32_32x32x16_bf16 v[96:111], v[80:83], v[112:115], v[32:47]
	v_xor_b32_e32 v192, 0x18000, v192
	v_exp_f32_e32 v64, v64
	v_exp_f32_e32 v65, v65
	v_exp_f32_e32 v66, v66
	v_exp_f32_e32 v67, v67
	v_exp_f32_e32 v68, v68
	v_exp_f32_e32 v69, v69
	v_exp_f32_e32 v74, v74
	s_add_u32 m0, s101, 0x2000
	s_waitcnt lgkmcnt(10)
	v_mfma_f32_32x32x16_bf16 v[80:95], v[138:141], v[112:115], v[32:47]
	global_load_lds_dwordx4 v[128:129], off
	v_exp_f32_e32 v138, v70
	v_exp_f32_e32 v139, v71
	v_exp_f32_e32 v140, v72
	v_exp_f32_e32 v141, v73
	v_exp_f32_e32 v75, v75
	v_exp_f32_e32 v70, v76
	v_exp_f32_e32 v71, v77
	s_add_u32 m0, s101, 0x4000
	s_waitcnt lgkmcnt(9)
	v_mfma_f32_32x32x16_bf16 v[96:111], v[152:155], v[116:119], v[96:111]
	global_load_lds_dwordx4 v[150:151], off
	v_exp_f32_e32 v152, v54
	v_exp_f32_e32 v153, v55
	v_cvt_pk_bf16_f32 v54, v68, v69
	v_cvt_pk_bf16_f32 v55, v138, v139
	v_exp_f32_e32 v72, v78
	v_exp_f32_e32 v73, v79
	v_exp_f32_e32 v48, v48
	s_mov_b32 m0, s101
	s_waitcnt lgkmcnt(8)
	v_mfma_f32_32x32x16_bf16 v[80:95], v[156:159], v[116:119], v[80:95]
	global_load_lds_dwordx4 v[130:131], off
	v_exp_f32_e32 v158, v52
	v_exp_f32_e32 v159, v53
	v_cvt_pk_bf16_f32 v52, v64, v65
	v_cvt_pk_bf16_f32 v53, v66, v67
	v_exp_f32_e32 v49, v49
	v_exp_f32_e32 v50, v50
	v_exp_f32_e32 v51, v51
	s_add_u32 m0, s101, 0x6000
	s_waitcnt lgkmcnt(3)
	v_mfma_f32_32x32x16_bf16 v[16:31], v[186:189], v[52:55], v[16:31]
	global_load_lds_dwordx4 v[132:133], off
	s_xor_b32 s101, s101, 0x18000
	v_exp_f32_e32 v154, v56
	v_exp_f32_e32 v155, v57
	v_exp_f32_e32 v156, v58
	v_exp_f32_e32 v157, v59
	v_pk_add_f32 v[56:57], v[136:137], v[64:65]
	s_waitcnt lgkmcnt(2)
	v_mfma_f32_32x32x16_bf16 v[0:15], v[194:197], v[52:55], v[0:15]
	v_cvt_pk_bf16_f32 v52, v140, v141
	v_cvt_pk_bf16_f32 v53, v74, v75
	v_cvt_pk_bf16_f32 v54, v70, v71
	v_cvt_pk_bf16_f32 v55, v72, v73
	v_add_f32_e64 v56, v66, v56
	v_add_f32_e64 v57, v67, v57
	v_pk_add_f32 v[56:57], v[68:69], v[56:57]
	v_mfma_f32_32x32x16_bf16 v[96:111], v[160:163], v[120:123], v[96:111]
	v_exp_f32_e32 v160, v60
	v_exp_f32_e32 v161, v61
	v_exp_f32_e32 v162, v62
	v_exp_f32_e32 v163, v63
	v_pk_add_f32 v[56:57], v[138:139], v[56:57]
	s_nop 0
	v_pk_add_f32 v[56:57], v[140:141], v[56:57]
	v_mfma_f32_32x32x16_bf16 v[80:95], v[174:177], v[120:123], v[80:95]
	v_add_f32_e64 v56, v74, v56
	v_add_f32_e64 v57, v75, v57
	v_add_f32_e64 v56, v70, v56
	v_add_f32_e64 v57, v71, v57
	v_add_f32_e64 v56, v72, v56
	v_add_f32_e64 v57, v73, v57
	s_waitcnt lgkmcnt(1)
	v_mfma_f32_32x32x16_bf16 v[16:31], v[198:201], v[52:55], v[16:31]
	s_waitcnt lgkmcnt(0)
	v_mfma_f32_32x32x16_bf16 v[0:15], v[204:207], v[52:55], v[0:15]
	v_cvt_pk_bf16_f32 v52, v48, v49
	v_cvt_pk_bf16_f32 v53, v50, v51
	v_cvt_pk_bf16_f32 v54, v158, v159
	v_cvt_pk_bf16_f32 v55, v152, v153
	v_add_f32_e64 v48, v48, v56
	v_add_f32_e64 v49, v49, v57
	v_pk_add_f32 v[190:191], v[50:51], v[48:49]
	v_mfma_f32_32x32x16_bf16 v[96:111], v[178:181], v[124:127], v[96:111]
	v_mfma_f32_32x32x16_bf16 v[80:95], v[182:185], v[124:127], v[80:95]
	ds_read_b128 v[174:177], v142 offset:16384
	ds_read_b128 v[178:181], v142 offset:20480
	ds_read_b128 v[182:185], v143 offset:16384
	ds_read_b128 v[210:213], v143 offset:20480
	s_waitcnt lgkmcnt(3)
	v_mfma_f32_32x32x16_bf16 v[16:31], v[174:177], v[52:55], v[16:31]
	s_waitcnt lgkmcnt(2)
	v_mfma_f32_32x32x16_bf16 v[0:15], v[178:181], v[52:55], v[0:15]
	v_cvt_pk_bf16_f32 v52, v154, v155
	v_cvt_pk_bf16_f32 v53, v156, v157
	v_cvt_pk_bf16_f32 v54, v160, v161
	v_cvt_pk_bf16_f32 v55, v162, v163
	s_nop 1
	s_waitcnt lgkmcnt(1)
	v_mfma_f32_32x32x16_bf16 v[16:31], v[182:185], v[52:55], v[16:31]
	s_waitcnt lgkmcnt(0)
	v_mfma_f32_32x32x16_bf16 v[0:15], v[210:213], v[52:55], v[0:15]
	ds_read_b128 v[52:55], v171
	ds_read_b128 v[174:177], v172
	ds_read_b128 v[178:181], v142
	ds_read_b128 v[182:185], v143
	ds_read_b128 v[186:189], v171 offset:4096
	ds_read_b128 v[194:197], v172 offset:4096
	ds_read_b128 v[198:201], v142 offset:4096
	ds_read_b128 v[204:207], v143 offset:4096
	ds_read_b128 v[210:213], v171 offset:24576
	ds_read_b128 v[214:217], v171 offset:28672
	ds_read_b128 v[218:221], v172 offset:24576
	ds_read_b128 v[222:225], v172 offset:28672
	v_exp_f32_e32 v96, v96
	v_exp_f32_e32 v97, v97
	v_exp_f32_e32 v98, v98
	v_exp_f32_e32 v99, v99
	v_exp_f32_e32 v100, v100
	v_exp_f32_e32 v101, v101
	v_exp_f32_e32 v102, v102
	v_exp_f32_e32 v103, v103
	v_pk_add_f32 v[158:159], v[158:159], v[190:191]
	s_waitcnt lgkmcnt(11)
	v_mfma_f32_32x32x16_bf16 v[64:79], v[52:55], v[112:115], v[32:47]
	v_add_f32_e64 v152, v152, v158
	v_add_f32_e64 v153, v153, v159
	v_exp_f32_e32 v104, v104
	v_pk_add_f32 v[152:153], v[154:155], v[152:153]
	v_exp_f32_e32 v154, v80
	v_pk_add_f32 v[152:153], v[156:157], v[152:153]
	v_exp_f32_e32 v155, v81
	v_exp_f32_e32 v156, v82
	v_exp_f32_e32 v157, v83
	v_cvt_pk_bf16_f32 v80, v96, v97
	v_cvt_pk_bf16_f32 v81, v98, v99
	v_cvt_pk_bf16_f32 v82, v100, v101
	v_cvt_pk_bf16_f32 v83, v102, v103
	s_waitcnt lgkmcnt(7)
	v_mfma_f32_32x32x16_bf16 v[48:63], v[186:189], v[112:115], v[32:47]
	v_exp_f32_e32 v105, v105
	v_exp_f32_e32 v106, v106
	v_exp_f32_e32 v107, v107
	v_exp_f32_e32 v108, v108
	v_exp_f32_e32 v109, v109
	v_exp_f32_e32 v110, v110
	v_exp_f32_e32 v111, v111
	s_waitcnt lgkmcnt(3)
	v_mfma_f32_32x32x16_bf16 v[16:31], v[210:213], v[80:83], v[16:31]
	v_exp_f32_e32 v84, v84
	v_exp_f32_e32 v85, v85
	v_exp_f32_e32 v86, v86
	v_exp_f32_e32 v87, v87
	v_pk_add_f32 v[152:153], v[160:161], v[152:153]
	v_exp_f32_e32 v88, v88
	v_pk_add_f32 v[152:153], v[162:163], v[152:153]
	s_waitcnt lgkmcnt(2)
	v_mfma_f32_32x32x16_bf16 v[0:15], v[214:217], v[80:83], v[0:15]
	v_cvt_pk_bf16_f32 v80, v104, v105
	v_cvt_pk_bf16_f32 v81, v106, v107
	v_cvt_pk_bf16_f32 v82, v108, v109
	v_cvt_pk_bf16_f32 v83, v110, v111
	v_add_f32_e64 v152, v152, v96
	v_add_f32_e64 v153, v153, v97
	v_exp_f32_e32 v89, v89
	v_exp_f32_e32 v90, v90
	v_mfma_f32_32x32x16_bf16 v[64:79], v[174:177], v[116:119], v[64:79]
	v_exp_f32_e32 v91, v91
	v_exp_f32_e32 v92, v92
	v_exp_f32_e32 v93, v93
	v_exp_f32_e32 v94, v94
	v_exp_f32_e32 v95, v95
	v_pk_add_f32 v[152:153], v[98:99], v[152:153]
	v_lshl_add_u64 v[150:151], v[150:151], 0, s[96:97]
	s_waitcnt lgkmcnt(1)
	v_mfma_f32_32x32x16_bf16 v[16:31], v[218:221], v[80:83], v[16:31]
	v_add_f32_e64 v152, v100, v152
	v_add_f32_e64 v153, v101, v153
	s_cmpk_lt_u32 s9, 0x42
	v_add_f32_e64 v152, v102, v152
	v_add_f32_e64 v153, v103, v153
	v_pk_add_f32 v[152:153], v[104:105], v[152:153]
	s_waitcnt lgkmcnt(0)
	v_mfma_f32_32x32x16_bf16 v[0:15], v[222:225], v[80:83], v[0:15]
	v_cvt_pk_bf16_f32 v80, v154, v155
	v_cvt_pk_bf16_f32 v81, v156, v157
	v_cvt_pk_bf16_f32 v82, v84, v85
	v_cvt_pk_bf16_f32 v83, v86, v87
	v_mfma_f32_32x32x16_bf16 v[48:63], v[194:197], v[116:119], v[48:63]
	v_mfma_f32_32x32x16_bf16 v[64:79], v[178:181], v[120:123], v[64:79]
	ds_read_b128 v[172:175], v142 offset:24576
	ds_read_b128 v[176:179], v142 offset:28672
	ds_read_b128 v[136:139], v143 offset:24576
	ds_read_b128 v[140:143], v143 offset:28672
	s_waitcnt lgkmcnt(3)
	v_mfma_f32_32x32x16_bf16 v[16:31], v[172:175], v[80:83], v[16:31]
	s_waitcnt lgkmcnt(2)
	v_mfma_f32_32x32x16_bf16 v[0:15], v[176:179], v[80:83], v[0:15]
	v_cvt_pk_bf16_f32 v80, v88, v89
	v_cvt_pk_bf16_f32 v81, v90, v91
	v_cvt_pk_bf16_f32 v82, v92, v93
	v_cvt_pk_bf16_f32 v83, v94, v95
	v_mfma_f32_32x32x16_bf16 v[48:63], v[198:201], v[120:123], v[48:63]
	s_waitcnt lgkmcnt(1)
	v_mfma_f32_32x32x16_bf16 v[16:31], v[136:139], v[80:83], v[16:31]
	s_waitcnt lgkmcnt(0)
	v_mfma_f32_32x32x16_bf16 v[0:15], v[140:143], v[80:83], v[0:15]
	v_add_f32_e64 v80, v106, v152
	v_add_f32_e64 v81, v107, v153
	v_add_f32_e64 v80, v108, v80
	v_add_f32_e64 v81, v109, v81
	v_add_f32_e64 v80, v110, v80
	v_add_f32_e64 v81, v111, v81
	v_pk_add_f32 v[80:81], v[154:155], v[80:81]
	v_mfma_f32_32x32x16_bf16 v[64:79], v[182:185], v[124:127], v[64:79]
	v_add_f32_e64 v80, v156, v80
	v_add_f32_e64 v81, v157, v81
	v_add_f32_e64 v80, v84, v80
	v_add_f32_e64 v81, v85, v81
	v_add_f32_e64 v80, v86, v80
	v_add_f32_e64 v81, v87, v81
	v_pk_add_f32 v[80:81], v[88:89], v[80:81]
	v_mfma_f32_32x32x16_bf16 v[48:63], v[204:207], v[124:127], v[48:63]
	v_add_f32_e64 v80, v90, v80
	v_add_f32_e64 v81, v91, v81
	v_add_f32_e64 v80, v92, v80
	v_add_f32_e64 v81, v93, v81
	v_add_f32_e64 v136, v94, v80
	v_add_f32_e64 v137, v95, v81
	s_cbranch_scc1 .LBB0_164
; DI unsigned pk2(float a, float b) { f32x2 v = {a, b}; bf2_t r = __builtin_convertvector(v, bf2_t); return __builtin_bit_cast(unsigned, r); }
; DI void attn_unit(const Params& p, int l, int b, int kvh, int qb, bool isctx, ldsp_t smem) {
;     ...
;     const float lrun = rs0 + rs1;
;     const float ltot = lrun + __shfl_xor(lrun, 32);
;     const float inv = 1.f / ltot;
; #pragma unroll
;     for (int dt = 0; dt < 2; ++dt)
; #pragma unroll
;         for (int g4 = 0; g4 < 4; ++g4) {
;             u32x2 w; w[0] = pk2(o[dt][4 * g4 + 0] * inv, o[dt][4 * g4 + 1] * inv); w[1] = pk2(o[dt][4 * g4 + 2] * inv, o[dt][4 * g4 + 3] * inv);
;             *(u32x2*)(Op + (size_t)r * DM + dt * 32 + 8 * g4 + 4 * hh) = w;
;         }
;     __syncthreads();
	s_waitcnt vmcnt(0)
	v_lshrrev_b32_e32 v42, 6, v252
	v_mul_u32_u24_e32 v42, 0x1200, v42
	v_add_u32_e32 v42, 0x8000, v42
	v_and_b32_e32 v43, 31, v252
	v_mul_u32_u24_e32 v43, 0x90, v43
	v_bfe_u32 v40, v252, 5, 1
	v_lshl_add_u32 v40, v40, 3, v43
	v_add_u32_e32 v40, v42, v40
	v_bfe_u32 v43, v252, 3, 3
	v_mul_u32_u24_e32 v43, 0x90, v43
	v_and_b32_e32 v41, 7, v252
	v_lshl_add_u32 v41, v41, 4, v43
	v_add_u32_e32 v41, v42, v41
	v_lshl_add_u32 v32, s7, 12, v144
	v_ashrrev_i32_e32 v33, 31, v32
	v_lshlrev_b64 v[32:33], 11, v[32:33]
	v_lshlrev_b32_e32 v34, 6, v166
	v_lshl_add_u64 v[32:33], s[18:19], 0, v[32:33]
	v_ashrrev_i32_e32 v35, 31, v34
	v_cmp_lt_i32_e32 vcc, v209, v203
	v_lshl_add_u64 v[32:33], v[34:35], 1, v[32:33]
	v_add_f32_e32 v34, v137, v136
	v_cndmask_b32_e32 v35, v202, v209, vcc
	v_lshlrev_b32_e32 v35, 2, v35
	ds_bpermute_b32 v35, v35, v34
	v_bfe_u32 v192, v252, 3, 3
	v_lshlrev_b32_e32 v192, 11, v192
	v_lshl_add_u64 v[32:33], v[32:33], 0, v[192:193]
	v_and_b32_e32 v192, 7, v252
	v_lshlrev_b32_e32 v192, 4, v192
	v_lshl_add_u64 v[32:33], v[32:33], 0, v[192:193]
	s_waitcnt lgkmcnt(0)
	v_add_f32_e32 v34, v34, v35
	v_div_scale_f32 v35, s[10:11], v34, v34, 1.0
	v_rcp_f32_e32 v36, v35
	s_nop 0
	v_fma_f32 v37, -v35, v36, 1.0
	v_fmac_f32_e32 v36, v37, v36
	v_div_scale_f32 v37, vcc, 1.0, v34, 1.0
	v_mul_f32_e32 v38, v37, v36
	v_fma_f32 v39, -v35, v38, v37
	v_fmac_f32_e32 v38, v39, v36
	v_fma_f32 v35, -v35, v38, v37
	v_div_fmas_f32 v35, v35, v36, v38
	v_div_fixup_f32 v34, v35, v34, 1.0
	v_pk_mul_f32 v[16:17], v[16:17], v[34:35] op_sel_hi:[1,0]
	v_pk_mul_f32 v[18:19], v[18:19], v[34:35] op_sel_hi:[1,0]
	v_pk_mul_f32 v[0:1], v[0:1], v[34:35] op_sel_hi:[1,0]
	v_pk_mul_f32 v[2:3], v[2:3], v[34:35] op_sel_hi:[1,0]
	v_cvt_pk_bf16_f32 v16, v16, v17
	v_cvt_pk_bf16_f32 v17, v18, v19
	v_cvt_pk_bf16_f32 v0, v0, v1
	v_cvt_pk_bf16_f32 v1, v2, v3
	ds_write_b64 v40, v[16:17]
	v_pk_mul_f32 v[16:17], v[20:21], v[34:35] op_sel_hi:[1,0]
	v_pk_mul_f32 v[18:19], v[22:23], v[34:35] op_sel_hi:[1,0]
	ds_write_b64 v40, v[0:1] offset:64
	v_pk_mul_f32 v[0:1], v[4:5], v[34:35] op_sel_hi:[1,0]
	v_pk_mul_f32 v[2:3], v[6:7], v[34:35] op_sel_hi:[1,0]
	v_cvt_pk_bf16_f32 v16, v16, v17
	v_cvt_pk_bf16_f32 v17, v18, v19
	v_cvt_pk_bf16_f32 v0, v0, v1
	v_cvt_pk_bf16_f32 v1, v2, v3
	ds_write_b64 v40, v[16:17] offset:16
	v_pk_mul_f32 v[16:17], v[24:25], v[34:35] op_sel_hi:[1,0]
	v_pk_mul_f32 v[18:19], v[26:27], v[34:35] op_sel_hi:[1,0]
	ds_write_b64 v40, v[0:1] offset:80
	v_pk_mul_f32 v[0:1], v[8:9], v[34:35] op_sel_hi:[1,0]
	v_pk_mul_f32 v[2:3], v[10:11], v[34:35] op_sel_hi:[1,0]
	v_cvt_pk_bf16_f32 v16, v16, v17
	v_cvt_pk_bf16_f32 v17, v18, v19
	v_cvt_pk_bf16_f32 v0, v0, v1
	v_cvt_pk_bf16_f32 v1, v2, v3
	ds_write_b64 v40, v[16:17] offset:32
	v_pk_mul_f32 v[16:17], v[28:29], v[34:35] op_sel_hi:[1,0]
	v_pk_mul_f32 v[18:19], v[30:31], v[34:35] op_sel_hi:[1,0]
	ds_write_b64 v40, v[0:1] offset:96
	v_pk_mul_f32 v[0:1], v[12:13], v[34:35] op_sel_hi:[1,0]
	v_pk_mul_f32 v[2:3], v[14:15], v[34:35] op_sel_hi:[1,0]
	v_cvt_pk_bf16_f32 v16, v16, v17
	v_cvt_pk_bf16_f32 v17, v18, v19
	v_cvt_pk_bf16_f32 v0, v0, v1
	v_cvt_pk_bf16_f32 v1, v2, v3
	ds_write_b64 v40, v[16:17] offset:48
	ds_write_b64 v40, v[0:1] offset:112
	ds_read_b128 v[44:47], v41
	ds_read_b128 v[48:51], v41 offset:1152
	ds_read_b128 v[52:55], v41 offset:2304
	ds_read_b128 v[56:59], v41 offset:3456
	v_mov_b32_e32 v192, 0x4000
	v_lshl_add_u64 v[60:61], v[32:33], 0, v[192:193]
	v_lshl_add_u64 v[62:63], v[60:61], 0, v[192:193]
	v_lshl_add_u64 v[64:65], v[62:63], 0, v[192:193]
	s_waitcnt lgkmcnt(0)
	global_store_dwordx4 v[32:33], v[44:47], off sc1
	global_store_dwordx4 v[60:61], v[48:51], off sc1
	global_store_dwordx4 v[62:63], v[52:55], off sc1
	global_store_dwordx4 v[64:65], v[56:59], off sc1
	s_barrier
	s_load_dword s7, s[88:89], 0x0
	s_waitcnt lgkmcnt(0)
	s_add_i32 s6, s7, s6
	s_cmpk_gt_i32 s6, 0x1ff
	s_cbranch_scc0 .LBB0_163
